# czero extended to the P1 in-proj K-loop (peeled first trip with C=0 first touches; p1skip skip paths zero the accumulators they would have started)
# baseline (speedup 1.0000x reference)
; #define PG8_STAGE(bufoff, gbase, voff) do { _Pragma("unroll") for (int _i = 0; _i < 2; ++_i) \
;         __builtin_amdgcn_global_load_lds((const unsigned*)((const char*)(gbase) + (voff)[_i]), (PG8_LAS unsigned*)(lds + (bufoff) + ldsw + _i * 8192), 16, 0, 0); } while (0)
; #define PG8_LDA(dst, b, h) do { _Pragma("unroll") for (int m = 0; m < 4; ++m) _Pragma("unroll") for (int k = 0; k < 2; ++k) dst[m][k] = *(const PG8_LAS bf16x8*)(lds + PG8_SA(b, h) + aoff + m * 2048 + k * 1024); } while (0)
; #define PG8_LDB(dst, b, h) do { _Pragma("unroll") for (int n = 0; n < 2; ++n) _Pragma("unroll") for (int k = 0; k < 2; ++k) dst[n][k] = *(const PG8_LAS bf16x8*)(lds + PG8_SB(b, h) + boff + n * 2048 + k * 1024); } while (0)
; #define PG8_MMA(ai, bj, At, Bt) do { __builtin_amdgcn_s_setprio(1); _Pragma("unroll") for (int m = 0; m < 4; ++m) _Pragma("unroll") for (int n = 0; n < 2; ++n) _Pragma("unroll") for (int k = 0; k < 2; ++k) \
;         acc[ai][bj][m][n] = __builtin_amdgcn_mfma_f32_16x16x32_bf16(Bt[n][k], At[m][k], acc[ai][bj][m][n], 0, 0, 0); __builtin_amdgcn_s_setprio(0); } while (0)
; #define PG8_WAIT_V(n) asm volatile("s_waitcnt vmcnt(" #n ")" ::: "memory")
; #define PG8_WAIT_L(n) asm volatile("s_waitcnt lgkmcnt(" #n ")" ::: "memory")
; #define PG8_BAR __builtin_amdgcn_s_barrier()
; #define PG8_SCHED __builtin_amdgcn_sched_barrier(0)
; template <class Epi, class Sched, bool ALIGN_EPI = false, bool SP2 = false>
; __device__ __forceinline__ void gemm_phase(PG8_LAS unsigned char* lds, const Gemm g, const Sched& S, const Epi& E) {
;     ...
;             PG8_LDB(B0, 0, 0); PG8_LDB(B1, 0, 1); PG8_SCHED; PG8_LDA(At, 0, 0); PG8_STAGE(PG8_SA(1, 1), a1 + hstep, voffA);
;             PG8_WAIT_V(8); PG8_WAIT_L(0); PG8_BAR; PG8_MMA(0, 0, At, B0); PG8_MMA(0, 1, At, B1); PG8_BAR; PG8_SCHED;
;     ...
; #pragma unroll
;         for (int a = 0; a < 2; ++a)
; #pragma unroll
;             for (int b = 0; b < 2; ++b)
; #pragma unroll
;                 for (int m = 0; m < 4; ++m)
; #pragma unroll
;                     for (int n = 0; n < 2; ++n) acc[a][b][m][n] = (f32x4){0.f, 0.f, 0.f, 0.f};
.LBB0_214:
	s_andn2_b64 vcc, exec, s[56:57]
	s_cbranch_vccz .Lcz_go_216
	v_mov_b32_e32 v2, v0
	v_mov_b32_e32 v3, v0
	v_mov_b32_e32 v1, v0
	v_mov_b64_e32 v[128:129], v[2:3]
	v_mov_b64_e32 v[124:125], v[2:3]
	v_mov_b64_e32 v[112:113], v[2:3]
	v_mov_b64_e32 v[108:109], v[2:3]
	v_mov_b64_e32 v[96:97], v[2:3]
	v_mov_b64_e32 v[92:93], v[2:3]
	v_mov_b64_e32 v[80:81], v[2:3]
	v_mov_b64_e32 v[76:77], v[2:3]
	v_mov_b64_e32 v[120:121], v[2:3]
	v_mov_b64_e32 v[116:117], v[2:3]
	v_mov_b64_e32 v[104:105], v[2:3]
	v_mov_b64_e32 v[100:101], v[2:3]
	v_mov_b64_e32 v[88:89], v[2:3]
	v_mov_b64_e32 v[84:85], v[2:3]
	v_mov_b64_e32 v[72:73], v[2:3]
	v_mov_b64_e32 v[68:69], v[2:3]
	v_mov_b64_e32 v[64:65], v[2:3]
	v_mov_b64_e32 v[60:61], v[2:3]
	v_mov_b64_e32 v[48:49], v[2:3]
	v_mov_b64_e32 v[44:45], v[2:3]
	v_mov_b64_e32 v[32:33], v[2:3]
	v_mov_b64_e32 v[28:29], v[2:3]
	v_mov_b64_e32 v[16:17], v[2:3]
	v_mov_b64_e32 v[12:13], v[2:3]
	v_mov_b64_e32 v[56:57], v[2:3]
	v_mov_b64_e32 v[52:53], v[2:3]
	v_mov_b64_e32 v[40:41], v[2:3]
	v_mov_b64_e32 v[36:37], v[2:3]
	v_mov_b64_e32 v[24:25], v[2:3]
	v_mov_b64_e32 v[20:21], v[2:3]
	v_mov_b64_e32 v[8:9], v[2:3]
	v_mov_b64_e32 v[126:127], v[0:1]
	v_mov_b64_e32 v[122:123], v[0:1]
	v_mov_b64_e32 v[110:111], v[0:1]
	v_mov_b64_e32 v[106:107], v[0:1]
	v_mov_b64_e32 v[94:95], v[0:1]
	v_mov_b64_e32 v[90:91], v[0:1]
	v_mov_b64_e32 v[78:79], v[0:1]
	v_mov_b64_e32 v[74:75], v[0:1]
	v_mov_b64_e32 v[118:119], v[0:1]
	v_mov_b64_e32 v[114:115], v[0:1]
	v_mov_b64_e32 v[102:103], v[0:1]
	v_mov_b64_e32 v[98:99], v[0:1]
	v_mov_b64_e32 v[86:87], v[0:1]
	v_mov_b64_e32 v[82:83], v[0:1]
	v_mov_b64_e32 v[70:71], v[0:1]
	v_mov_b64_e32 v[66:67], v[0:1]
	v_mov_b64_e32 v[62:63], v[0:1]
	v_mov_b64_e32 v[58:59], v[0:1]
	v_mov_b64_e32 v[46:47], v[0:1]
	v_mov_b64_e32 v[42:43], v[0:1]
	v_mov_b64_e32 v[30:31], v[0:1]
	v_mov_b64_e32 v[26:27], v[0:1]
	v_mov_b64_e32 v[14:15], v[0:1]
	v_mov_b64_e32 v[10:11], v[0:1]
	v_mov_b64_e32 v[54:55], v[0:1]
	v_mov_b64_e32 v[50:51], v[0:1]
	v_mov_b64_e32 v[38:39], v[0:1]
	v_mov_b64_e32 v[34:35], v[0:1]
	v_mov_b64_e32 v[22:23], v[0:1]
	v_mov_b64_e32 v[18:19], v[0:1]
	v_mov_b64_e32 v[6:7], v[0:1]
	v_mov_b64_e32 v[4:5], v[2:3]
	v_mov_b64_e32 v[2:3], v[0:1]
	s_branch .LBB0_217
.Lcz_z0_216:
	v_mov_b32_e32 v126, 0
	v_mov_b32_e32 v127, 0
	v_mov_b32_e32 v128, 0
	v_mov_b32_e32 v129, 0
	v_mov_b32_e32 v122, 0
	v_mov_b32_e32 v123, 0
	v_mov_b32_e32 v124, 0
	v_mov_b32_e32 v125, 0
	v_mov_b32_e32 v110, 0
	v_mov_b32_e32 v111, 0
	v_mov_b32_e32 v112, 0
	v_mov_b32_e32 v113, 0
	v_mov_b32_e32 v106, 0
	v_mov_b32_e32 v107, 0
	v_mov_b32_e32 v108, 0
	v_mov_b32_e32 v109, 0
	v_mov_b32_e32 v94, 0
	v_mov_b32_e32 v95, 0
	v_mov_b32_e32 v96, 0
	v_mov_b32_e32 v97, 0
	v_mov_b32_e32 v90, 0
	v_mov_b32_e32 v91, 0
	v_mov_b32_e32 v92, 0
	v_mov_b32_e32 v93, 0
	v_mov_b32_e32 v78, 0
	v_mov_b32_e32 v79, 0
	v_mov_b32_e32 v80, 0
	v_mov_b32_e32 v81, 0
	v_mov_b32_e32 v74, 0
	v_mov_b32_e32 v75, 0
	v_mov_b32_e32 v76, 0
	v_mov_b32_e32 v77, 0
	v_mov_b32_e32 v118, 0
	v_mov_b32_e32 v119, 0
	v_mov_b32_e32 v120, 0
	v_mov_b32_e32 v121, 0
	v_mov_b32_e32 v114, 0
	v_mov_b32_e32 v115, 0
	v_mov_b32_e32 v116, 0
	v_mov_b32_e32 v117, 0
	v_mov_b32_e32 v102, 0
	v_mov_b32_e32 v103, 0
	v_mov_b32_e32 v104, 0
	v_mov_b32_e32 v105, 0
	v_mov_b32_e32 v98, 0
	v_mov_b32_e32 v99, 0
	v_mov_b32_e32 v100, 0
	v_mov_b32_e32 v101, 0
	v_mov_b32_e32 v86, 0
	v_mov_b32_e32 v87, 0
	v_mov_b32_e32 v88, 0
	v_mov_b32_e32 v89, 0
	v_mov_b32_e32 v82, 0
	v_mov_b32_e32 v83, 0
	v_mov_b32_e32 v84, 0
	v_mov_b32_e32 v85, 0
	v_mov_b32_e32 v70, 0
	v_mov_b32_e32 v71, 0
	v_mov_b32_e32 v72, 0
	v_mov_b32_e32 v73, 0
	v_mov_b32_e32 v66, 0
	v_mov_b32_e32 v67, 0
	v_mov_b32_e32 v68, 0
	v_mov_b32_e32 v69, 0
	s_branch .Lp1skip_0_pz
.Lcz_z1_216:
	v_mov_b32_e32 v62, 0
	v_mov_b32_e32 v63, 0
	v_mov_b32_e32 v64, 0
	v_mov_b32_e32 v65, 0
	v_mov_b32_e32 v58, 0
	v_mov_b32_e32 v59, 0
	v_mov_b32_e32 v60, 0
	v_mov_b32_e32 v61, 0
	v_mov_b32_e32 v46, 0
	v_mov_b32_e32 v47, 0
	v_mov_b32_e32 v48, 0
	v_mov_b32_e32 v49, 0
	v_mov_b32_e32 v42, 0
	v_mov_b32_e32 v43, 0
	v_mov_b32_e32 v44, 0
	v_mov_b32_e32 v45, 0
	v_mov_b32_e32 v30, 0
	v_mov_b32_e32 v31, 0
	v_mov_b32_e32 v32, 0
	v_mov_b32_e32 v33, 0
	v_mov_b32_e32 v26, 0
	v_mov_b32_e32 v27, 0
	v_mov_b32_e32 v28, 0
	v_mov_b32_e32 v29, 0
	v_mov_b32_e32 v14, 0
	v_mov_b32_e32 v15, 0
	v_mov_b32_e32 v16, 0
	v_mov_b32_e32 v17, 0
	v_mov_b32_e32 v10, 0
	v_mov_b32_e32 v11, 0
	v_mov_b32_e32 v12, 0
	v_mov_b32_e32 v13, 0
	v_mov_b32_e32 v54, 0
	v_mov_b32_e32 v55, 0
	v_mov_b32_e32 v56, 0
	v_mov_b32_e32 v57, 0
	v_mov_b32_e32 v50, 0
	v_mov_b32_e32 v51, 0
	v_mov_b32_e32 v52, 0
	v_mov_b32_e32 v53, 0
	v_mov_b32_e32 v38, 0
	v_mov_b32_e32 v39, 0
	v_mov_b32_e32 v40, 0
	v_mov_b32_e32 v41, 0
	v_mov_b32_e32 v34, 0
	v_mov_b32_e32 v35, 0
	v_mov_b32_e32 v36, 0
	v_mov_b32_e32 v37, 0
	v_mov_b32_e32 v22, 0
	v_mov_b32_e32 v23, 0
	v_mov_b32_e32 v24, 0
	v_mov_b32_e32 v25, 0
	v_mov_b32_e32 v18, 0
	v_mov_b32_e32 v19, 0
	v_mov_b32_e32 v20, 0
	v_mov_b32_e32 v21, 0
	v_mov_b32_e32 v6, 0
	v_mov_b32_e32 v7, 0
	v_mov_b32_e32 v8, 0
	v_mov_b32_e32 v9, 0
	v_mov_b32_e32 v2, 0
	v_mov_b32_e32 v3, 0
	v_mov_b32_e32 v4, 0
	v_mov_b32_e32 v5, 0
	s_branch .Lp1skip_1_pz
; #define PG8_STAGE(bufoff, gbase, voff) do { _Pragma("unroll") for (int _i = 0; _i < 2; ++_i) \
;         __builtin_amdgcn_global_load_lds((const unsigned*)((const char*)(gbase) + (voff)[_i]), (PG8_LAS unsigned*)(lds + (bufoff) + ldsw + _i * 8192), 16, 0, 0); } while (0)
; #define PG8_LDA(dst, b, h) do { _Pragma("unroll") for (int m = 0; m < 4; ++m) _Pragma("unroll") for (int k = 0; k < 2; ++k) dst[m][k] = *(const PG8_LAS bf16x8*)(lds + PG8_SA(b, h) + aoff + m * 2048 + k * 1024); } while (0)
; #define PG8_LDB(dst, b, h) do { _Pragma("unroll") for (int n = 0; n < 2; ++n) _Pragma("unroll") for (int k = 0; k < 2; ++k) dst[n][k] = *(const PG8_LAS bf16x8*)(lds + PG8_SB(b, h) + boff + n * 2048 + k * 1024); } while (0)
; #define PG8_MMA(ai, bj, At, Bt) do { __builtin_amdgcn_s_setprio(1); _Pragma("unroll") for (int m = 0; m < 4; ++m) _Pragma("unroll") for (int n = 0; n < 2; ++n) _Pragma("unroll") for (int k = 0; k < 2; ++k) \
;         acc[ai][bj][m][n] = __builtin_amdgcn_mfma_f32_16x16x32_bf16(Bt[n][k], At[m][k], acc[ai][bj][m][n], 0, 0, 0); __builtin_amdgcn_s_setprio(0); } while (0)
; #define PG8_WAIT_V(n) asm volatile("s_waitcnt vmcnt(" #n ")" ::: "memory")
; #define PG8_WAIT_L(n) asm volatile("s_waitcnt lgkmcnt(" #n ")" ::: "memory")
; #define PG8_BAR __builtin_amdgcn_s_barrier()
; #define PG8_SCHED __builtin_amdgcn_sched_barrier(0)
; template <class Epi, class Sched, bool ALIGN_EPI = false, bool SP2 = false>
; __device__ __forceinline__ void gemm_phase(PG8_LAS unsigned char* lds, const Gemm g, const Sched& S, const Epi& E) {
;     ...
;         for (int t = 0; t < nt; t += 2) {
;             const bool last = (t == nt - 2);
;             const char* a1 = cA + (size_t)(t + 1) * kstep;
;             const char* a2 = last ? nA : cA + (size_t)(t + 2) * kstep; const char* b2 = last ? nB : cB + (size_t)(t + 2) * kstep;
;             const char* a3 = a2 + kstep; const char* b3 = b2 + kstep;
;             if (last && has_next) S.a_ready(nxt);
;             if constexpr (SP2) {
;             PG8_LDB(B0, 0, 0); PG8_LDB(B1, 0, 1); PG8_SCHED; PG8_LDA(At, 0, 0); PG8_STAGE(PG8_SA(1, 1), a1 + hstep, voffA);
;             PG8_WAIT_V(8); PG8_WAIT_L(0); PG8_BAR; PG8_MMA(0, 0, At, B0); PG8_MMA(0, 1, At, B1); PG8_BAR; PG8_SCHED;
.Lcz_go_216:
	v_mov_b32_e32 v1, 0
	s_cmp_eq_u32 s48, 0x100
	s_cselect_b32 s100, 1, 0
	s_cmp_eq_u32 s49, 26
	s_cselect_b32 s101, s99, 0
	s_or_b32 s100, s100, s101
	s_add_u32 s0, s72, 0x80
	s_addc_u32 s1, s73, 0
	s_add_u32 s61, s6, 0x100
	s_addc_u32 s72, s7, 0
	s_mov_b32 s6, 0
	ds_read_b128 v[130:133], v178
	ds_read_b128 v[134:137], v178 offset:1024
	ds_read_b128 v[138:141], v178 offset:2048
	ds_read_b128 v[142:145], v178 offset:3072
	ds_read_b128 v[168:171], v179
	ds_read_b128 v[172:175], v179 offset:1024
	ds_read_b128 v[182:185], v179 offset:2048
	ds_read_b128 v[186:189], v179 offset:3072
	s_add_i32 s73, s6, 2
	s_add_u32 vcc_lo, s0, 0x80
	s_addc_u32 s7, s1, 0
	s_cmp_eq_u32 s92, s6
	s_cselect_b32 s6, s62, vcc_lo
	s_cselect_b32 s7, s63, s7
	s_cselect_b32 vcc_hi, s71, s72
	s_cselect_b32 vcc_lo, s70, s61
	v_lshl_add_u64 v[198:199], s[0:1], 0, v[160:161]
	s_add_i32 m0, s77, 0xc000
	ds_read_b128 v[190:193], v180
	ds_read_b128 v[194:197], v180 offset:1024
	ds_read_b128 v[202:205], v180 offset:2048
	ds_read_b128 v[206:209], v180 offset:3072
	ds_read_b128 v[210:213], v180 offset:4096
	ds_read_b128 v[214:217], v180 offset:5120
	ds_read_b128 v[218:221], v180 offset:6144
	ds_read_b128 v[222:225], v180 offset:7168
	global_load_lds_dwordx4 v[198:199], off
	v_lshl_add_u64 v[198:199], s[0:1], 0, v[162:163]
	s_add_i32 m0, s77, 0xe000
	s_nop 0
	global_load_lds_dwordx4 v[198:199], off
	s_waitcnt vmcnt(8)
	s_waitcnt lgkmcnt(0)
	s_barrier
	s_setprio 1
	s_waitcnt lgkmcnt(0)
	s_bitcmp1_b32 s100, 1
	s_cbranch_scc1 .Lcz_z0_216
	v_mfma_f32_16x16x32_bf16 v[126:129], v[130:133], v[190:193], 0
	v_mfma_f32_16x16x32_bf16 v[122:125], v[138:141], v[190:193], 0
	v_mfma_f32_16x16x32_bf16 v[110:113], v[130:133], v[202:205], 0
	v_mfma_f32_16x16x32_bf16 v[106:109], v[138:141], v[202:205], 0
	v_mfma_f32_16x16x32_bf16 v[94:97], v[130:133], v[210:213], 0
	v_mfma_f32_16x16x32_bf16 v[90:93], v[138:141], v[210:213], 0
	v_mfma_f32_16x16x32_bf16 v[78:81], v[130:133], v[218:221], 0
	v_mfma_f32_16x16x32_bf16 v[74:77], v[138:141], v[218:221], 0
	v_mfma_f32_16x16x32_bf16 v[126:129], v[134:137], v[194:197], v[126:129]
	v_mfma_f32_16x16x32_bf16 v[122:125], v[142:145], v[194:197], v[122:125]
	v_mfma_f32_16x16x32_bf16 v[110:113], v[134:137], v[206:209], v[110:113]
	v_mfma_f32_16x16x32_bf16 v[106:109], v[142:145], v[206:209], v[106:109]
	v_mfma_f32_16x16x32_bf16 v[94:97], v[134:137], v[214:217], v[94:97]
	v_mfma_f32_16x16x32_bf16 v[90:93], v[142:145], v[214:217], v[90:93]
	v_mfma_f32_16x16x32_bf16 v[78:81], v[134:137], v[222:225], v[78:81]
	v_mfma_f32_16x16x32_bf16 v[74:77], v[142:145], v[222:225], v[74:77]
	s_setprio 0
	s_setprio 1
	v_mfma_f32_16x16x32_bf16 v[118:121], v[168:171], v[190:193], 0
	v_mfma_f32_16x16x32_bf16 v[114:117], v[182:185], v[190:193], 0
	v_mfma_f32_16x16x32_bf16 v[102:105], v[168:171], v[202:205], 0
	v_mfma_f32_16x16x32_bf16 v[98:101], v[182:185], v[202:205], 0
	v_mfma_f32_16x16x32_bf16 v[86:89], v[168:171], v[210:213], 0
	v_mfma_f32_16x16x32_bf16 v[82:85], v[182:185], v[210:213], 0
	v_mfma_f32_16x16x32_bf16 v[70:73], v[168:171], v[218:221], 0
	v_mfma_f32_16x16x32_bf16 v[66:69], v[182:185], v[218:221], 0
	v_mfma_f32_16x16x32_bf16 v[118:121], v[172:175], v[194:197], v[118:121]
	v_mfma_f32_16x16x32_bf16 v[114:117], v[186:189], v[194:197], v[114:117]
	v_mfma_f32_16x16x32_bf16 v[102:105], v[172:175], v[206:209], v[102:105]
	v_mfma_f32_16x16x32_bf16 v[98:101], v[186:189], v[206:209], v[98:101]
	v_mfma_f32_16x16x32_bf16 v[86:89], v[172:175], v[214:217], v[86:89]
	v_mfma_f32_16x16x32_bf16 v[82:85], v[186:189], v[214:217], v[82:85]
	v_mfma_f32_16x16x32_bf16 v[70:73], v[172:175], v[222:225], v[70:73]
	v_mfma_f32_16x16x32_bf16 v[66:69], v[186:189], v[222:225], v[66:69]
; #define PG8_STAGE(bufoff, gbase, voff) do { _Pragma("unroll") for (int _i = 0; _i < 2; ++_i) \
;         __builtin_amdgcn_global_load_lds((const unsigned*)((const char*)(gbase) + (voff)[_i]), (PG8_LAS unsigned*)(lds + (bufoff) + ldsw + _i * 8192), 16, 0, 0); } while (0)
; #define PG8_LDA(dst, b, h) do { _Pragma("unroll") for (int m = 0; m < 4; ++m) _Pragma("unroll") for (int k = 0; k < 2; ++k) dst[m][k] = *(const PG8_LAS bf16x8*)(lds + PG8_SA(b, h) + aoff + m * 2048 + k * 1024); } while (0)
; #define PG8_MMA(ai, bj, At, Bt) do { __builtin_amdgcn_s_setprio(1); _Pragma("unroll") for (int m = 0; m < 4; ++m) _Pragma("unroll") for (int n = 0; n < 2; ++n) _Pragma("unroll") for (int k = 0; k < 2; ++k) \
;         acc[ai][bj][m][n] = __builtin_amdgcn_mfma_f32_16x16x32_bf16(Bt[n][k], At[m][k], acc[ai][bj][m][n], 0, 0, 0); __builtin_amdgcn_s_setprio(0); } while (0)
; #define PG8_WAIT_V(n) asm volatile("s_waitcnt vmcnt(" #n ")" ::: "memory")
; #define PG8_WAIT_L(n) asm volatile("s_waitcnt lgkmcnt(" #n ")" ::: "memory")
; #define PG8_BAR __builtin_amdgcn_s_barrier()
; #define PG8_SCHED __builtin_amdgcn_sched_barrier(0)
; template <class Epi, class Sched, bool ALIGN_EPI = false, bool SP2 = false>
; __device__ __forceinline__ void gemm_phase(PG8_LAS unsigned char* lds, const Gemm g, const Sched& S, const Epi& E) {
;     ...
;             PG8_LDA(At, 0, 1); PG8_STAGE(PG8_SB(0, 0), b2, voffB); PG8_STAGE(PG8_SB(0, 1), b2 + hstep, voffB); PG8_STAGE(PG8_SA(0, 0), a2, voffA);
;             PG8_WAIT_V(8); PG8_WAIT_L(0); PG8_BAR; PG8_MMA(1, 0, At, B0); PG8_MMA(1, 1, At, B1); PG8_BAR; PG8_SCHED;
.Lp1skip_0_pz:
	s_setprio 0
	s_barrier
	s_add_i32 s16, s96, s76
	v_lshl_add_u64 v[198:199], vcc, 0, v[148:149]
	s_mov_b32 m0, s16
	ds_read_b128 v[190:193], v180 offset:16384
	ds_read_b128 v[194:197], v180 offset:17408
	ds_read_b128 v[202:205], v180 offset:18432
	ds_read_b128 v[206:209], v180 offset:19456
	ds_read_b128 v[210:213], v180 offset:20480
	ds_read_b128 v[214:217], v180 offset:21504
	ds_read_b128 v[218:221], v180 offset:22528
	ds_read_b128 v[222:225], v180 offset:23552
	global_load_lds_dwordx4 v[198:199], off
	s_add_i32 m0, s16, 0x2000
	v_lshl_add_u64 v[226:227], vcc, 0, v[152:153]
	s_add_u32 vcc_lo, vcc_lo, s10
	s_addc_u32 vcc_hi, vcc_hi, s11
	s_add_i32 s16, s97, s76
	global_load_lds_dwordx4 v[226:227], off
	v_lshl_add_u64 v[228:229], vcc, 0, v[148:149]
	s_mov_b32 m0, s16
	v_lshl_add_u64 v[230:231], vcc, 0, v[152:153]
	global_load_lds_dwordx4 v[228:229], off
	s_add_i32 m0, s16, 0x2000
	v_lshl_add_u64 v[232:233], s[6:7], 0, v[146:147]
	global_load_lds_dwordx4 v[230:231], off
	s_mov_b32 m0, s77
	v_lshl_add_u64 v[236:237], s[6:7], 0, v[150:151]
	global_load_lds_dwordx4 v[232:233], off
	s_mov_b32 m0, s78
	s_nop 0
	global_load_lds_dwordx4 v[236:237], off
	s_waitcnt vmcnt(8)
	s_waitcnt lgkmcnt(0)
	s_barrier
	s_setprio 1
	s_waitcnt lgkmcnt(0)
	s_bitcmp1_b32 s100, 0
	s_cbranch_scc1 .Lcz_z1_216
	v_mfma_f32_16x16x32_bf16 v[62:65], v[130:133], v[190:193], 0
	v_mfma_f32_16x16x32_bf16 v[58:61], v[138:141], v[190:193], 0
	v_mfma_f32_16x16x32_bf16 v[46:49], v[130:133], v[202:205], 0
	v_mfma_f32_16x16x32_bf16 v[42:45], v[138:141], v[202:205], 0
	v_mfma_f32_16x16x32_bf16 v[30:33], v[130:133], v[210:213], 0
	v_mfma_f32_16x16x32_bf16 v[26:29], v[138:141], v[210:213], 0
	v_mfma_f32_16x16x32_bf16 v[14:17], v[130:133], v[218:221], 0
	v_mfma_f32_16x16x32_bf16 v[10:13], v[138:141], v[218:221], 0
	v_mfma_f32_16x16x32_bf16 v[62:65], v[134:137], v[194:197], v[62:65]
	v_mfma_f32_16x16x32_bf16 v[58:61], v[142:145], v[194:197], v[58:61]
	v_mfma_f32_16x16x32_bf16 v[46:49], v[134:137], v[206:209], v[46:49]
	v_mfma_f32_16x16x32_bf16 v[42:45], v[142:145], v[206:209], v[42:45]
	v_mfma_f32_16x16x32_bf16 v[30:33], v[134:137], v[214:217], v[30:33]
	v_mfma_f32_16x16x32_bf16 v[26:29], v[142:145], v[214:217], v[26:29]
	v_mfma_f32_16x16x32_bf16 v[14:17], v[134:137], v[222:225], v[14:17]
	v_mfma_f32_16x16x32_bf16 v[10:13], v[142:145], v[222:225], v[10:13]
	s_setprio 0
	s_setprio 1
	v_mfma_f32_16x16x32_bf16 v[54:57], v[168:171], v[190:193], 0
	v_mfma_f32_16x16x32_bf16 v[50:53], v[182:185], v[190:193], 0
	v_mfma_f32_16x16x32_bf16 v[38:41], v[168:171], v[202:205], 0
	v_mfma_f32_16x16x32_bf16 v[34:37], v[182:185], v[202:205], 0
	v_mfma_f32_16x16x32_bf16 v[22:25], v[168:171], v[210:213], 0
	v_mfma_f32_16x16x32_bf16 v[18:21], v[182:185], v[210:213], 0
	v_mfma_f32_16x16x32_bf16 v[6:9], v[168:171], v[218:221], 0
	v_mfma_f32_16x16x32_bf16 v[2:5], v[182:185], v[218:221], 0
	v_mfma_f32_16x16x32_bf16 v[54:57], v[172:175], v[194:197], v[54:57]
	v_mfma_f32_16x16x32_bf16 v[50:53], v[186:189], v[194:197], v[50:53]
	v_mfma_f32_16x16x32_bf16 v[38:41], v[172:175], v[206:209], v[38:41]
	v_mfma_f32_16x16x32_bf16 v[34:37], v[186:189], v[206:209], v[34:37]
	v_mfma_f32_16x16x32_bf16 v[22:25], v[172:175], v[214:217], v[22:25]
	v_mfma_f32_16x16x32_bf16 v[18:21], v[186:189], v[214:217], v[18:21]
	v_mfma_f32_16x16x32_bf16 v[6:9], v[172:175], v[222:225], v[6:9]
	v_mfma_f32_16x16x32_bf16 v[2:5], v[186:189], v[222:225], v[2:5]

; #define PG8_MMA(ai, bj, At, Bt) do { __builtin_amdgcn_s_setprio(1); _Pragma("unroll") for (int m = 0; m < 4; ++m) _Pragma("unroll") for (int n = 0; n < 2; ++n) _Pragma("unroll") for (int k = 0; k < 2; ++k) \
;         acc[ai][bj][m][n] = __builtin_amdgcn_mfma_f32_16x16x32_bf16(Bt[n][k], At[m][k], acc[ai][bj][m][n], 0, 0, 0); __builtin_amdgcn_s_setprio(0); } while (0)
; #define PG8_WAIT_V(n) asm volatile("s_waitcnt vmcnt(" #n ")" ::: "memory")
; #define PG8_WAIT_L(n) asm volatile("s_waitcnt lgkmcnt(" #n ")" ::: "memory")
; #define PG8_BAR __builtin_amdgcn_s_barrier()
; #define PG8_SCHED __builtin_amdgcn_sched_barrier(0)
; template <class Epi, class Sched, bool ALIGN_EPI = false, bool SP2 = false>
; __device__ __forceinline__ void gemm_phase(PG8_LAS unsigned char* lds, const Gemm g, const Sched& S, const Epi& E) {
;     ...
;         for (int t = 0; t < nt; t += 2) {
;             const bool last = (t == nt - 2);
;     ...
;             PG8_WAIT_V(8); PG8_WAIT_L(0); PG8_BAR; PG8_MMA(1, 0, At, B0); PG8_MMA(1, 1, At, B1); PG8_BAR; PG8_SCHED;
.Lp1skip_3_pz:
	s_setprio 0
	s_barrier
	s_add_u32 s0, s0, 0x100
	s_addc_u32 s1, s1, 0
	s_add_u32 s61, s61, 0x100
	s_addc_u32 s72, s72, 0
	s_cmp_ge_i32 s73, s84
	s_mov_b32 s6, s73
	s_cbranch_scc1 .LBB0_217
